# P0 row loop software-pipelined (3 rows in flight); later code kept at its baseline placement mod 256 bytes
# speedup vs baseline: 1.0048x; 1.0048x over previous
; __global__ void __launch_bounds__(512, 2) fwd_megakernel(Args a) {
;     ...
;     if (IN(0)) for (int rep = (PROBE_DUP == 0 ? 0 : 1); rep < 2; ++rep) { p0_phase(lds, a, vcu, G, wave, lane); __syncthreads(); }
.LBB0_62:
	s_nop 0
	s_nop 0
	s_nop 0
	s_nop 0
	s_nop 0
	s_nop 0
	s_nop 0
	s_nop 0
	s_nop 0
	s_nop 0
	s_nop 0
	s_nop 0
	s_nop 0
	s_nop 0
	s_nop 0
	s_nop 0
	s_nop 0
	s_nop 0
	s_nop 0
	s_nop 0
	s_nop 0
	s_nop 0
	s_nop 0
	s_nop 0
	s_nop 0
	s_nop 0
	s_nop 0
	s_waitcnt lgkmcnt(0)
	s_barrier
